# DOWN layer-1 epilogue (single round per CU): write-through sc1 stores so the following grid barrier finds less dirty L2
# speedup vs baseline: 1.0030x; 1.0030x over previous
.LBB0_1532:
	s_lshr_b32 s33, s19, 3
	s_cmp_lt_i32 s19, 64
	s_mulk_i32 s33, 0x1800
	s_cselect_b32 s50, s33, 0xc000
	s_ashr_i32 s51, s50, 31
	s_lshl_b32 s19, s19, 8
	s_add_i32 s19, s19, s10
	s_lshl_b64 s[48:49], s[50:51], 2
	s_add_u32 s33, s26, s48
	s_addc_u32 s49, s27, s49
	v_mov_b32_e32 v132, v0
	s_add_u32 s48, s33, 0x5000
	s_addc_u32 s49, s49, 0
	v_lshrrev_b32_e32 v133, 1, v132
	s_lshl_b32 s18, s18, 8
	v_and_or_b32 v133, v133, 24, s18
	v_or_b32_e32 v196, s11, v133
	s_add_i32 s18, s50, 0x1000
	v_lshlrev_b32_e32 v144, 2, v196
	v_add_lshl_u32 v152, v196, s18, 2
	v_and_or_b32 v156, v132, 15, s19
	global_load_dwordx4 v[132:135], v144, s[48:49] offset:16
	global_load_dwordx4 v[136:139], v144, s[48:49]
	global_load_dwordx4 v[214:217], v144, s[42:43] offset:16
	s_nop 0
	global_load_dwordx4 v[218:221], v144, s[42:43]
	s_nop 0
	global_load_dwordx4 v[222:225], v152, s[26:27] offset:16
	s_nop 0
	global_load_dwordx4 v[226:229], v152, s[26:27]
	v_lshlrev_b32_e32 v189, 1, v196
	v_lshlrev_b32_e32 v197, 11, v156
	v_add_u32_e32 v188, v189, v197
	global_load_dwordx4 v[204:207], v188, s[96:97] nt
	v_or_b32_e32 v198, 0x8000, v197
	v_or_b32_e32 v190, 0x10000, v197
	v_or_b32_e32 v191, 0x18000, v197
	v_add_u32_e32 v192, 0x40000, v197
	v_add_u32_e32 v193, 0x48000, v197
	v_add_u32_e32 v194, 0x50000, v197
	v_add_u32_e32 v195, 0x58000, v197
	s_and_b64 vcc, exec, s[38:39]
	v_add_u32_e32 v140, v189, v198
	global_load_dwordx4 v[164:167], v140, s[96:97] nt
	v_add_u32_e32 v140, v189, v190
	global_load_dwordx4 v[160:163], v140, s[96:97] nt
	v_add_u32_e32 v140, v189, v191
	global_load_dwordx4 v[156:159], v140, s[96:97] nt
	v_add_u32_e32 v140, v189, v192
	global_load_dwordx4 v[152:155], v140, s[96:97] nt
	v_add_u32_e32 v140, v189, v193
	global_load_dwordx4 v[148:151], v140, s[96:97] nt
	v_add_u32_e32 v140, v189, v194
	global_load_dwordx4 v[144:147], v140, s[96:97] nt
	v_add_u32_e32 v140, v189, v195
	global_load_dwordx4 v[140:143], v140, s[96:97] nt
	s_waitcnt vmcnt(7)
	v_pk_add_f32 v[228:229], v[228:229], 1.0 op_sel_hi:[1,0]
	s_nop 0
	v_pk_mul_f32 v[220:221], v[220:221], v[228:229]
	v_pk_add_f32 v[226:227], v[226:227], 1.0 op_sel_hi:[1,0]
	v_rcp_f32_e32 v182, v220
	v_rcp_f32_e32 v183, v221
	v_pk_add_f32 v[220:221], v[222:223], 1.0 op_sel_hi:[1,0]
	v_pk_mul_f32 v[218:219], v[218:219], v[226:227]
	v_pk_mul_f32 v[214:215], v[214:215], v[220:221]
	v_rcp_f32_e32 v178, v218
	v_rcp_f32_e32 v180, v214
	v_rcp_f32_e32 v179, v219
	v_pk_add_f32 v[218:219], v[224:225], 1.0 op_sel_hi:[1,0]
	v_pk_mul_f32 v[184:185], v[216:217], v[218:219]
	v_rcp_f32_e32 v181, v215
	v_rcp_f32_e32 v184, v184
	v_rcp_f32_e32 v185, v185
	v_lshlrev_b32_e32 v208, 16, v204
	v_and_b32_e32 v209, 0xffff0000, v204
	v_lshlrev_b32_e32 v204, 16, v205
	v_and_b32_e32 v205, 0xffff0000, v205
	v_lshlrev_b32_e32 v210, 16, v206
	v_and_b32_e32 v211, 0xffff0000, v206
	v_lshlrev_b32_e32 v206, 16, v207
	v_and_b32_e32 v207, 0xffff0000, v207
	v_pk_mul_f32 v[204:205], v[182:183], v[204:205]
	v_pk_mul_f32 v[208:209], v[178:179], v[208:209]
	v_pk_mul_f32 v[206:207], v[184:185], v[206:207]
	v_pk_mul_f32 v[210:211], v[180:181], v[210:211]
	v_pk_fma_f32 v[130:131], v[130:131], v[138:139], v[204:205]
	v_pk_fma_f32 v[128:129], v[128:129], v[136:137], v[208:209]
	v_pk_fma_f32 v[204:205], v[126:127], v[134:135], v[206:207]
	v_pk_fma_f32 v[206:207], v[124:125], v[132:133], v[210:211]
	v_mov_b32_e32 v126, v129
	v_mov_b32_e32 v127, v207
	v_mov_b32_e32 v124, v128
	v_mov_b32_e32 v125, v206
	v_pk_mul_f32 v[126:127], v[126:127], v[126:127]
	v_mov_b32_e32 v208, v131
	v_mov_b32_e32 v209, v205
	v_pk_fma_f32 v[124:125], v[124:125], v[124:125], v[126:127]
	v_mov_b32_e32 v126, v130
	v_mov_b32_e32 v127, v204
	v_pk_mul_f32 v[208:209], v[208:209], v[208:209]
	s_nop 0
	v_pk_fma_f32 v[126:127], v[126:127], v[126:127], v[208:209]
	s_nop 0
	v_pk_add_f32 v[124:125], v[124:125], v[126:127]
	v_cvt_pk_bf16_f32 v126, v128, v129
	v_add_f32_e32 v124, v124, v125
	v_cvt_pk_bf16_f32 v127, v130, v131
	v_cvt_pk_bf16_f32 v128, v206, v207
	v_cvt_pk_bf16_f32 v129, v204, v205
	global_store_dwordx4 v188, v[126:129], s[96:97] sc1
	v_add_u32_e32 v125, 0x8000, v188
	s_waitcnt vmcnt(7)
	v_lshlrev_b32_e32 v130, 16, v166
	v_lshlrev_b32_e32 v126, 16, v164
	v_and_b32_e32 v127, 0xffff0000, v164
	v_lshlrev_b32_e32 v128, 16, v165
	v_and_b32_e32 v129, 0xffff0000, v165
	v_and_b32_e32 v131, 0xffff0000, v166
	v_lshlrev_b32_e32 v164, 16, v167
	v_and_b32_e32 v165, 0xffff0000, v167
	v_pk_mul_f32 v[128:129], v[182:183], v[128:129]
	v_pk_mul_f32 v[126:127], v[178:179], v[126:127]
	v_pk_mul_f32 v[130:131], v[180:181], v[130:131]
	v_pk_mul_f32 v[164:165], v[184:185], v[164:165]
	v_pk_fma_f32 v[122:123], v[122:123], v[138:139], v[128:129]
	v_pk_fma_f32 v[120:121], v[120:121], v[136:137], v[126:127]
	v_pk_fma_f32 v[128:129], v[116:117], v[132:133], v[130:131]
	v_pk_fma_f32 v[126:127], v[118:119], v[134:135], v[164:165]
	v_mov_b32_e32 v118, v121
	v_mov_b32_e32 v119, v129
	v_mov_b32_e32 v116, v120
	v_mov_b32_e32 v117, v128
	v_pk_mul_f32 v[118:119], v[118:119], v[118:119]
	v_mov_b32_e32 v130, v123
	v_mov_b32_e32 v131, v127
	v_pk_fma_f32 v[116:117], v[116:117], v[116:117], v[118:119]
	v_mov_b32_e32 v118, v122
	v_mov_b32_e32 v119, v126
	v_pk_mul_f32 v[130:131], v[130:131], v[130:131]
	s_nop 0
	v_pk_fma_f32 v[118:119], v[118:119], v[118:119], v[130:131]
	s_nop 0
	v_pk_add_f32 v[116:117], v[116:117], v[118:119]
	v_cvt_pk_bf16_f32 v118, v120, v121
	v_add_f32_e32 v116, v116, v117
	v_cvt_pk_bf16_f32 v119, v122, v123
	v_cvt_pk_bf16_f32 v120, v128, v129
	v_cvt_pk_bf16_f32 v121, v126, v127
	global_store_dwordx4 v125, v[118:121], s[96:97] sc1
	s_waitcnt vmcnt(7)
	v_lshlrev_b32_e32 v122, 16, v162
	v_and_b32_e32 v123, 0xffff0000, v162
	v_lshlrev_b32_e32 v118, 16, v160
	v_and_b32_e32 v119, 0xffff0000, v160
	v_lshlrev_b32_e32 v120, 16, v161
	v_and_b32_e32 v121, 0xffff0000, v161
	v_lshlrev_b32_e32 v126, 16, v163
	v_and_b32_e32 v127, 0xffff0000, v163
	v_pk_mul_f32 v[120:121], v[182:183], v[120:121]
	v_pk_mul_f32 v[118:119], v[178:179], v[118:119]
	v_pk_mul_f32 v[122:123], v[180:181], v[122:123]
	v_pk_mul_f32 v[126:127], v[184:185], v[126:127]
	v_pk_fma_f32 v[114:115], v[114:115], v[138:139], v[120:121]
	v_pk_fma_f32 v[112:113], v[112:113], v[136:137], v[118:119]
	v_pk_fma_f32 v[120:121], v[108:109], v[132:133], v[122:123]
	v_pk_fma_f32 v[118:119], v[110:111], v[134:135], v[126:127]
	v_mov_b32_e32 v110, v113
	v_mov_b32_e32 v111, v121
	v_mov_b32_e32 v108, v112
	v_mov_b32_e32 v109, v120
	v_pk_mul_f32 v[110:111], v[110:111], v[110:111]
	v_mov_b32_e32 v122, v115
	v_mov_b32_e32 v123, v119
	v_pk_fma_f32 v[108:109], v[108:109], v[108:109], v[110:111]
	v_mov_b32_e32 v110, v114
	v_mov_b32_e32 v111, v118
	v_pk_mul_f32 v[122:123], v[122:123], v[122:123]
	v_add_u32_e32 v117, 0x10000, v188
	v_pk_fma_f32 v[110:111], v[110:111], v[110:111], v[122:123]
	s_nop 0
	v_pk_add_f32 v[108:109], v[108:109], v[110:111]
	v_cvt_pk_bf16_f32 v110, v112, v113
	v_add_f32_e32 v108, v108, v109
	v_cvt_pk_bf16_f32 v111, v114, v115
	v_cvt_pk_bf16_f32 v112, v120, v121
	v_cvt_pk_bf16_f32 v113, v118, v119
	global_store_dwordx4 v117, v[110:113], s[96:97] sc1
	s_waitcnt vmcnt(7)
	v_lshlrev_b32_e32 v114, 16, v158
	v_and_b32_e32 v115, 0xffff0000, v158
	v_lshlrev_b32_e32 v110, 16, v156
	v_and_b32_e32 v111, 0xffff0000, v156
	v_lshlrev_b32_e32 v112, 16, v157
	v_and_b32_e32 v113, 0xffff0000, v157
	v_lshlrev_b32_e32 v118, 16, v159
	v_and_b32_e32 v119, 0xffff0000, v159
	v_pk_mul_f32 v[112:113], v[182:183], v[112:113]
	v_pk_mul_f32 v[110:111], v[178:179], v[110:111]
	v_pk_mul_f32 v[118:119], v[184:185], v[118:119]
	v_pk_mul_f32 v[114:115], v[180:181], v[114:115]
	v_pk_fma_f32 v[106:107], v[106:107], v[138:139], v[112:113]
	v_pk_fma_f32 v[110:111], v[104:105], v[136:137], v[110:111]
	v_pk_fma_f32 v[112:113], v[102:103], v[134:135], v[118:119]
	v_pk_fma_f32 v[102:103], v[100:101], v[132:133], v[114:115]
	v_mov_b32_e32 v104, v111
	v_mov_b32_e32 v105, v103
	v_mov_b32_e32 v100, v110
	v_mov_b32_e32 v101, v102
	v_pk_mul_f32 v[104:105], v[104:105], v[104:105]
	v_mov_b32_e32 v114, v107
	v_mov_b32_e32 v115, v113
	v_pk_fma_f32 v[100:101], v[100:101], v[100:101], v[104:105]
	v_mov_b32_e32 v104, v106
	v_mov_b32_e32 v105, v112
	v_pk_mul_f32 v[114:115], v[114:115], v[114:115]
	v_add_u32_e32 v109, 0x18000, v188
	v_pk_fma_f32 v[104:105], v[104:105], v[104:105], v[114:115]
	v_cvt_pk_bf16_f32 v102, v102, v103
	v_pk_add_f32 v[100:101], v[100:101], v[104:105]
	v_cvt_pk_bf16_f32 v103, v112, v113
	v_add_f32_e32 v104, v100, v101
	v_cvt_pk_bf16_f32 v100, v110, v111
	v_cvt_pk_bf16_f32 v101, v106, v107
	global_store_dwordx4 v109, v[100:103], s[96:97] sc1
	s_waitcnt vmcnt(7)
	v_lshlrev_b32_e32 v106, 16, v154
	v_and_b32_e32 v107, 0xffff0000, v154
	v_lshlrev_b32_e32 v100, 16, v152
	v_and_b32_e32 v101, 0xffff0000, v152
	v_lshlrev_b32_e32 v110, 16, v155
	v_and_b32_e32 v111, 0xffff0000, v155
	v_lshlrev_b32_e32 v102, 16, v153
	v_and_b32_e32 v103, 0xffff0000, v153
	v_pk_mul_f32 v[100:101], v[178:179], v[100:101]
	v_pk_mul_f32 v[110:111], v[184:185], v[110:111]
	v_pk_mul_f32 v[106:107], v[180:181], v[106:107]
	v_pk_mul_f32 v[102:103], v[182:183], v[102:103]
	v_pk_fma_f32 v[94:95], v[94:95], v[136:137], v[100:101]
	v_pk_fma_f32 v[100:101], v[92:93], v[134:135], v[110:111]
	v_pk_fma_f32 v[92:93], v[90:91], v[132:133], v[106:107]
	v_pk_fma_f32 v[96:97], v[96:97], v[138:139], v[102:103]
	v_mov_b32_e32 v102, v95
	v_mov_b32_e32 v103, v93
	v_mov_b32_e32 v90, v94
	v_mov_b32_e32 v91, v92
	v_pk_mul_f32 v[102:103], v[102:103], v[102:103]
	v_mov_b32_e32 v106, v97
	v_mov_b32_e32 v107, v101
	v_pk_fma_f32 v[90:91], v[90:91], v[90:91], v[102:103]
	v_mov_b32_e32 v102, v96
	v_mov_b32_e32 v103, v100
	v_pk_mul_f32 v[106:107], v[106:107], v[106:107]
	v_add_u32_e32 v105, 0x40000, v188
	v_pk_fma_f32 v[102:103], v[102:103], v[102:103], v[106:107]
	v_cvt_pk_bf16_f32 v92, v92, v93
	v_pk_add_f32 v[90:91], v[90:91], v[102:103]
	v_cvt_pk_bf16_f32 v93, v100, v101
	v_add_f32_e32 v103, v90, v91
	v_cvt_pk_bf16_f32 v90, v94, v95
	v_cvt_pk_bf16_f32 v91, v96, v97
	global_store_dwordx4 v105, v[90:93], s[96:97] sc1
	s_waitcnt vmcnt(7)
	v_lshlrev_b32_e32 v94, 16, v150
	v_and_b32_e32 v95, 0xffff0000, v150
	v_lshlrev_b32_e32 v90, 16, v148
	v_and_b32_e32 v91, 0xffff0000, v148
	v_lshlrev_b32_e32 v96, 16, v151
	v_and_b32_e32 v97, 0xffff0000, v151
	v_lshlrev_b32_e32 v92, 16, v149
	v_and_b32_e32 v93, 0xffff0000, v149
	v_pk_mul_f32 v[90:91], v[178:179], v[90:91]
	v_pk_mul_f32 v[96:97], v[184:185], v[96:97]
	v_pk_mul_f32 v[94:95], v[180:181], v[94:95]
	v_pk_mul_f32 v[92:93], v[182:183], v[92:93]
	v_pk_fma_f32 v[86:87], v[86:87], v[136:137], v[90:91]
	v_pk_fma_f32 v[90:91], v[84:85], v[134:135], v[96:97]
	v_pk_fma_f32 v[84:85], v[82:83], v[132:133], v[94:95]
	v_pk_fma_f32 v[88:89], v[88:89], v[138:139], v[92:93]
	v_mov_b32_e32 v92, v87
	v_mov_b32_e32 v93, v85
	v_mov_b32_e32 v82, v86
	v_mov_b32_e32 v83, v84
	v_pk_mul_f32 v[92:93], v[92:93], v[92:93]
	v_mov_b32_e32 v94, v89
	v_mov_b32_e32 v95, v91
	v_pk_fma_f32 v[82:83], v[82:83], v[82:83], v[92:93]
	v_mov_b32_e32 v92, v88
	v_mov_b32_e32 v93, v90
	v_pk_mul_f32 v[94:95], v[94:95], v[94:95]
	v_add_u32_e32 v100, 0x48000, v188
	v_pk_fma_f32 v[92:93], v[92:93], v[92:93], v[94:95]
	v_cvt_pk_bf16_f32 v84, v84, v85
	v_pk_add_f32 v[82:83], v[82:83], v[92:93]
	v_cvt_pk_bf16_f32 v85, v90, v91
	v_add_f32_e32 v102, v82, v83
	v_cvt_pk_bf16_f32 v82, v86, v87
	v_cvt_pk_bf16_f32 v83, v88, v89
	global_store_dwordx4 v100, v[82:85], s[96:97] sc1
	s_waitcnt vmcnt(7)
	v_lshlrev_b32_e32 v86, 16, v146
	v_and_b32_e32 v87, 0xffff0000, v146
	v_lshlrev_b32_e32 v82, 16, v144
	v_and_b32_e32 v83, 0xffff0000, v144
	v_lshlrev_b32_e32 v88, 16, v147
	v_and_b32_e32 v89, 0xffff0000, v147
	v_lshlrev_b32_e32 v84, 16, v145
	v_and_b32_e32 v85, 0xffff0000, v145
	v_pk_mul_f32 v[82:83], v[178:179], v[82:83]
	v_pk_mul_f32 v[88:89], v[184:185], v[88:89]
	v_pk_mul_f32 v[86:87], v[180:181], v[86:87]
	v_pk_mul_f32 v[84:85], v[182:183], v[84:85]
	v_pk_fma_f32 v[78:79], v[78:79], v[136:137], v[82:83]
	v_pk_fma_f32 v[82:83], v[76:77], v[134:135], v[88:89]
	v_pk_fma_f32 v[76:77], v[74:75], v[132:133], v[86:87]
	v_pk_fma_f32 v[80:81], v[80:81], v[138:139], v[84:85]
	v_mov_b32_e32 v84, v79
	v_mov_b32_e32 v85, v77
	v_mov_b32_e32 v74, v78
	v_mov_b32_e32 v75, v76
	v_pk_mul_f32 v[84:85], v[84:85], v[84:85]
	v_mov_b32_e32 v86, v81
	v_mov_b32_e32 v87, v83
	v_pk_fma_f32 v[74:75], v[74:75], v[74:75], v[84:85]
	v_mov_b32_e32 v84, v80
	v_mov_b32_e32 v85, v82
	v_pk_mul_f32 v[86:87], v[86:87], v[86:87]
	v_add_u32_e32 v90, 0x50000, v188
	v_pk_fma_f32 v[84:85], v[84:85], v[84:85], v[86:87]
	v_cvt_pk_bf16_f32 v76, v76, v77
	v_pk_add_f32 v[74:75], v[74:75], v[84:85]
	v_cvt_pk_bf16_f32 v77, v82, v83
	v_add_f32_e32 v101, v74, v75
	v_cvt_pk_bf16_f32 v74, v78, v79
	v_cvt_pk_bf16_f32 v75, v80, v81
	global_store_dwordx4 v90, v[74:77], s[96:97] sc1
	s_waitcnt vmcnt(7)
	v_lshlrev_b32_e32 v78, 16, v142
	v_and_b32_e32 v79, 0xffff0000, v142
	v_lshlrev_b32_e32 v74, 16, v140
	v_and_b32_e32 v75, 0xffff0000, v140
	v_lshlrev_b32_e32 v80, 16, v143
	v_and_b32_e32 v81, 0xffff0000, v143
	v_lshlrev_b32_e32 v76, 16, v141
	v_and_b32_e32 v77, 0xffff0000, v141
	v_pk_mul_f32 v[74:75], v[178:179], v[74:75]
	v_pk_mul_f32 v[80:81], v[184:185], v[80:81]
	v_pk_mul_f32 v[78:79], v[180:181], v[78:79]
	v_pk_mul_f32 v[76:77], v[182:183], v[76:77]
	v_pk_fma_f32 v[70:71], v[70:71], v[136:137], v[74:75]
	v_pk_fma_f32 v[74:75], v[68:69], v[134:135], v[80:81]
	v_pk_fma_f32 v[68:69], v[66:67], v[132:133], v[78:79]
	v_pk_fma_f32 v[72:73], v[72:73], v[138:139], v[76:77]
	v_mov_b32_e32 v76, v71
	v_mov_b32_e32 v77, v69
	v_mov_b32_e32 v66, v70
	v_mov_b32_e32 v67, v68
	v_pk_mul_f32 v[76:77], v[76:77], v[76:77]
	v_mov_b32_e32 v78, v73
	v_mov_b32_e32 v79, v75
	v_pk_fma_f32 v[66:67], v[66:67], v[66:67], v[76:77]
	v_mov_b32_e32 v76, v72
	v_mov_b32_e32 v77, v74
	v_pk_mul_f32 v[78:79], v[78:79], v[78:79]
	v_add_u32_e32 v82, 0x58000, v188
	v_pk_fma_f32 v[76:77], v[76:77], v[76:77], v[78:79]
	v_cvt_pk_bf16_f32 v68, v68, v69
	v_pk_add_f32 v[66:67], v[66:67], v[76:77]
	v_cvt_pk_bf16_f32 v69, v74, v75
	v_add_f32_e32 v100, v66, v67
	v_cvt_pk_bf16_f32 v66, v70, v71
	v_cvt_pk_bf16_f32 v67, v72, v73
	global_store_dwordx4 v82, v[66:69], s[96:97] sc1
	v_or_b32_e32 v82, 0x80, v196
	v_lshlrev_b32_e32 v78, 2, v82
	v_add_lshl_u32 v86, v82, s18, 2
	global_load_dwordx4 v[66:69], v78, s[48:49] offset:16
	global_load_dwordx4 v[70:73], v78, s[48:49]
	global_load_dwordx4 v[214:217], v78, s[42:43] offset:16
	s_nop 0
	global_load_dwordx4 v[218:221], v78, s[42:43]
	s_nop 0
	global_load_dwordx4 v[222:225], v86, s[26:27] offset:16
	s_nop 0
	global_load_dwordx4 v[226:229], v86, s[26:27]
	v_or_b32_e32 v105, 0x100, v188
	s_mov_b64 s[48:49], -1
	v_or_b32_e32 v74, 0x100, v189
	v_add_u32_e32 v75, v74, v197
	global_load_dwordx4 v[110:113], v75, s[96:97] nt
	v_add_u32_e32 v75, v74, v198
	global_load_dwordx4 v[118:121], v75, s[96:97] nt
	v_add_u32_e32 v75, v74, v190
	global_load_dwordx4 v[126:129], v75, s[96:97] nt
	v_add_u32_e32 v75, v74, v191
	global_load_dwordx4 v[130:133], v75, s[96:97] nt
	v_add_u32_e32 v75, v74, v192
	global_load_dwordx4 v[86:89], v75, s[96:97] nt
	v_add_u32_e32 v75, v74, v193
	global_load_dwordx4 v[82:85], v75, s[96:97] nt
	v_add_u32_e32 v75, v74, v194
	global_load_dwordx4 v[78:81], v75, s[96:97] nt
	v_add_u32_e32 v74, v74, v195
	global_load_dwordx4 v[74:77], v74, s[96:97] nt
	s_waitcnt vmcnt(8)
	v_pk_add_f32 v[228:229], v[228:229], 1.0 op_sel_hi:[1,0]
	s_nop 0
	v_pk_mul_f32 v[220:221], v[220:221], v[228:229]
	v_pk_add_f32 v[226:227], v[226:227], 1.0 op_sel_hi:[1,0]
	v_rcp_f32_e32 v94, v220
	v_rcp_f32_e32 v95, v221
	v_pk_add_f32 v[220:221], v[222:223], 1.0 op_sel_hi:[1,0]
	v_pk_mul_f32 v[218:219], v[218:219], v[226:227]
	v_pk_mul_f32 v[214:215], v[214:215], v[220:221]
	v_rcp_f32_e32 v90, v218
	v_rcp_f32_e32 v92, v214
	v_rcp_f32_e32 v93, v215
	v_rcp_f32_e32 v91, v219
	v_pk_add_f32 v[218:219], v[224:225], 1.0 op_sel_hi:[1,0]
	v_pk_mul_f32 v[96:97], v[216:217], v[218:219]
	v_rcp_f32_e32 v96, v96
	v_rcp_f32_e32 v97, v97
	s_waitcnt vmcnt(7)
	v_lshlrev_b32_e32 v106, 16, v110
	v_and_b32_e32 v107, 0xffff0000, v110
	v_lshlrev_b32_e32 v114, 16, v112
	v_and_b32_e32 v115, 0xffff0000, v112
	v_lshlrev_b32_e32 v112, 16, v113
	v_and_b32_e32 v113, 0xffff0000, v113
	v_lshlrev_b32_e32 v110, 16, v111
	v_and_b32_e32 v111, 0xffff0000, v111
	v_pk_mul_f32 v[106:107], v[90:91], v[106:107]
	v_pk_mul_f32 v[112:113], v[96:97], v[112:113]
	v_pk_mul_f32 v[114:115], v[92:93], v[114:115]
	v_pk_mul_f32 v[110:111], v[94:95], v[110:111]
	v_pk_fma_f32 v[62:63], v[62:63], v[70:71], v[106:107]
	v_pk_fma_f32 v[106:107], v[60:61], v[68:69], v[112:113]
	v_pk_fma_f32 v[60:61], v[58:59], v[66:67], v[114:115]
	v_pk_fma_f32 v[64:65], v[64:65], v[72:73], v[110:111]
	v_mov_b32_e32 v110, v63
	v_mov_b32_e32 v111, v61
	v_mov_b32_e32 v58, v62
	v_mov_b32_e32 v59, v60
	v_pk_mul_f32 v[110:111], v[110:111], v[110:111]
	v_mov_b32_e32 v112, v65
	v_mov_b32_e32 v113, v107
	v_pk_fma_f32 v[58:59], v[58:59], v[58:59], v[110:111]
	v_mov_b32_e32 v110, v64
	v_mov_b32_e32 v111, v106
	v_pk_mul_f32 v[112:113], v[112:113], v[112:113]
	v_cvt_pk_bf16_f32 v60, v60, v61
	v_pk_fma_f32 v[110:111], v[110:111], v[110:111], v[112:113]
	v_cvt_pk_bf16_f32 v61, v106, v107
	v_pk_add_f32 v[58:59], v[58:59], v[110:111]
	s_nop 0
	v_add_f32_e32 v58, v58, v59
	v_add_f32_e32 v58, v124, v58
	v_cvt_pk_bf16_f32 v59, v64, v65
	v_cvt_pk_bf16_f32 v58, v62, v63
	global_store_dwordx4 v105, v[58:61], s[96:97] sc1
	s_waitcnt vmcnt(7)
	v_lshlrev_b32_e32 v62, 16, v120
	v_and_b32_e32 v63, 0xffff0000, v120
	v_lshlrev_b32_e32 v58, 16, v118
	v_and_b32_e32 v59, 0xffff0000, v118
	v_lshlrev_b32_e32 v64, 16, v121
	v_and_b32_e32 v65, 0xffff0000, v121
	v_lshlrev_b32_e32 v60, 16, v119
	v_and_b32_e32 v61, 0xffff0000, v119
	v_pk_mul_f32 v[58:59], v[90:91], v[58:59]
	v_pk_mul_f32 v[64:65], v[96:97], v[64:65]
	v_pk_mul_f32 v[62:63], v[92:93], v[62:63]
	v_pk_mul_f32 v[60:61], v[94:95], v[60:61]
	v_pk_fma_f32 v[54:55], v[54:55], v[70:71], v[58:59]
	v_pk_fma_f32 v[58:59], v[52:53], v[68:69], v[64:65]
	v_pk_fma_f32 v[52:53], v[50:51], v[66:67], v[62:63]
	v_pk_fma_f32 v[56:57], v[56:57], v[72:73], v[60:61]
	v_mov_b32_e32 v60, v55
	v_mov_b32_e32 v61, v53
	v_mov_b32_e32 v50, v54
	v_mov_b32_e32 v51, v52
	v_pk_mul_f32 v[60:61], v[60:61], v[60:61]
	v_mov_b32_e32 v62, v57
	v_mov_b32_e32 v63, v59
	v_pk_fma_f32 v[50:51], v[50:51], v[50:51], v[60:61]
	v_mov_b32_e32 v60, v56
	v_mov_b32_e32 v61, v58
	v_pk_mul_f32 v[62:63], v[62:63], v[62:63]
	v_add_u32_e32 v105, 0x8100, v188
	v_pk_fma_f32 v[60:61], v[60:61], v[60:61], v[62:63]
	v_cvt_pk_bf16_f32 v52, v52, v53
	v_pk_add_f32 v[50:51], v[50:51], v[60:61]
	v_cvt_pk_bf16_f32 v53, v58, v59
	v_add_f32_e32 v50, v50, v51
	v_add_f32_e32 v50, v116, v50
	v_cvt_pk_bf16_f32 v51, v56, v57
	v_cvt_pk_bf16_f32 v50, v54, v55
	global_store_dwordx4 v105, v[50:53], s[96:97] sc1
	s_waitcnt vmcnt(7)
	v_lshlrev_b32_e32 v54, 16, v128
	v_and_b32_e32 v55, 0xffff0000, v128
	v_lshlrev_b32_e32 v50, 16, v126
	v_and_b32_e32 v51, 0xffff0000, v126
	v_lshlrev_b32_e32 v56, 16, v129
	v_and_b32_e32 v57, 0xffff0000, v129
	v_lshlrev_b32_e32 v52, 16, v127
	v_and_b32_e32 v53, 0xffff0000, v127
	v_pk_mul_f32 v[50:51], v[90:91], v[50:51]
	v_pk_mul_f32 v[56:57], v[96:97], v[56:57]
	v_pk_mul_f32 v[54:55], v[92:93], v[54:55]
	v_pk_mul_f32 v[52:53], v[94:95], v[52:53]
	v_pk_fma_f32 v[46:47], v[46:47], v[70:71], v[50:51]
	v_pk_fma_f32 v[50:51], v[44:45], v[68:69], v[56:57]
	v_pk_fma_f32 v[44:45], v[42:43], v[66:67], v[54:55]
	v_pk_fma_f32 v[48:49], v[48:49], v[72:73], v[52:53]
	v_mov_b32_e32 v52, v47
	v_mov_b32_e32 v53, v45
	v_mov_b32_e32 v42, v46
	v_mov_b32_e32 v43, v44
	v_pk_mul_f32 v[52:53], v[52:53], v[52:53]
	v_mov_b32_e32 v54, v49
	v_mov_b32_e32 v55, v51
	v_pk_fma_f32 v[42:43], v[42:43], v[42:43], v[52:53]
	v_mov_b32_e32 v52, v48
	v_mov_b32_e32 v53, v50
	v_pk_mul_f32 v[54:55], v[54:55], v[54:55]
	v_add_u32_e32 v58, 0x10100, v188
	v_pk_fma_f32 v[52:53], v[52:53], v[52:53], v[54:55]
	v_cvt_pk_bf16_f32 v44, v44, v45
	v_pk_add_f32 v[42:43], v[42:43], v[52:53]
	v_cvt_pk_bf16_f32 v45, v50, v51
	v_add_f32_e32 v42, v42, v43
	v_add_f32_e32 v42, v108, v42
	v_cvt_pk_bf16_f32 v43, v48, v49
	v_cvt_pk_bf16_f32 v42, v46, v47
	global_store_dwordx4 v58, v[42:45], s[96:97] sc1
	s_waitcnt vmcnt(7)
	v_lshlrev_b32_e32 v46, 16, v132
	v_and_b32_e32 v47, 0xffff0000, v132
	v_lshlrev_b32_e32 v42, 16, v130
	v_and_b32_e32 v43, 0xffff0000, v130
	v_lshlrev_b32_e32 v48, 16, v133
	v_and_b32_e32 v49, 0xffff0000, v133
	v_lshlrev_b32_e32 v44, 16, v131
	v_and_b32_e32 v45, 0xffff0000, v131
	v_pk_mul_f32 v[42:43], v[90:91], v[42:43]
	v_pk_mul_f32 v[48:49], v[96:97], v[48:49]
	v_pk_mul_f32 v[46:47], v[92:93], v[46:47]
	v_pk_mul_f32 v[44:45], v[94:95], v[44:45]
	v_pk_fma_f32 v[38:39], v[38:39], v[70:71], v[42:43]
	v_pk_fma_f32 v[42:43], v[36:37], v[68:69], v[48:49]
	v_pk_fma_f32 v[36:37], v[34:35], v[66:67], v[46:47]
	v_pk_fma_f32 v[40:41], v[40:41], v[72:73], v[44:45]
	v_mov_b32_e32 v44, v39
	v_mov_b32_e32 v45, v37
	v_mov_b32_e32 v34, v38
	v_mov_b32_e32 v35, v36
	v_pk_mul_f32 v[44:45], v[44:45], v[44:45]
	v_mov_b32_e32 v46, v41
	v_mov_b32_e32 v47, v43
	v_pk_fma_f32 v[34:35], v[34:35], v[34:35], v[44:45]
	v_mov_b32_e32 v44, v40
	v_mov_b32_e32 v45, v42
	v_pk_mul_f32 v[46:47], v[46:47], v[46:47]
	v_add_u32_e32 v50, 0x18100, v188
	v_pk_fma_f32 v[44:45], v[44:45], v[44:45], v[46:47]
	v_cvt_pk_bf16_f32 v36, v36, v37
	v_pk_add_f32 v[34:35], v[34:35], v[44:45]
	v_cvt_pk_bf16_f32 v37, v42, v43
	v_add_f32_e32 v34, v34, v35
	v_add_f32_e32 v34, v104, v34
	v_cvt_pk_bf16_f32 v35, v40, v41
	v_cvt_pk_bf16_f32 v34, v38, v39
	global_store_dwordx4 v50, v[34:37], s[96:97] sc1
	s_waitcnt vmcnt(7)
	v_lshlrev_b32_e32 v38, 16, v88
	v_and_b32_e32 v39, 0xffff0000, v88
	v_lshlrev_b32_e32 v34, 16, v86
	v_and_b32_e32 v35, 0xffff0000, v86
	v_lshlrev_b32_e32 v40, 16, v89
	v_and_b32_e32 v41, 0xffff0000, v89
	v_lshlrev_b32_e32 v36, 16, v87
	v_and_b32_e32 v37, 0xffff0000, v87
	v_pk_mul_f32 v[34:35], v[90:91], v[34:35]
	v_pk_mul_f32 v[40:41], v[96:97], v[40:41]
	v_pk_mul_f32 v[38:39], v[92:93], v[38:39]
	v_pk_mul_f32 v[36:37], v[94:95], v[36:37]
	v_pk_fma_f32 v[30:31], v[30:31], v[70:71], v[34:35]
	v_pk_fma_f32 v[34:35], v[28:29], v[68:69], v[40:41]
	v_pk_fma_f32 v[28:29], v[26:27], v[66:67], v[38:39]
	v_pk_fma_f32 v[32:33], v[32:33], v[72:73], v[36:37]
	v_mov_b32_e32 v36, v31
	v_mov_b32_e32 v37, v29
	v_mov_b32_e32 v26, v30
	v_mov_b32_e32 v27, v28
	v_pk_mul_f32 v[36:37], v[36:37], v[36:37]
	v_mov_b32_e32 v38, v33
	v_mov_b32_e32 v39, v35
	v_pk_fma_f32 v[26:27], v[26:27], v[26:27], v[36:37]
	v_mov_b32_e32 v36, v32
	v_mov_b32_e32 v37, v34
	v_pk_mul_f32 v[38:39], v[38:39], v[38:39]
	v_add_u32_e32 v42, 0x40100, v188
	v_pk_fma_f32 v[36:37], v[36:37], v[36:37], v[38:39]
	v_cvt_pk_bf16_f32 v28, v28, v29
	v_pk_add_f32 v[26:27], v[26:27], v[36:37]
	v_cvt_pk_bf16_f32 v29, v34, v35
	v_add_f32_e32 v26, v26, v27
	v_add_f32_e32 v26, v103, v26
	v_cvt_pk_bf16_f32 v27, v32, v33
	v_cvt_pk_bf16_f32 v26, v30, v31
	global_store_dwordx4 v42, v[26:29], s[96:97] sc1
	s_waitcnt vmcnt(7)
	v_lshlrev_b32_e32 v30, 16, v84
	v_and_b32_e32 v31, 0xffff0000, v84
	v_lshlrev_b32_e32 v26, 16, v82
	v_and_b32_e32 v27, 0xffff0000, v82
	v_lshlrev_b32_e32 v32, 16, v85
	v_and_b32_e32 v33, 0xffff0000, v85
	v_lshlrev_b32_e32 v28, 16, v83
	v_and_b32_e32 v29, 0xffff0000, v83
	v_pk_mul_f32 v[26:27], v[90:91], v[26:27]
	v_pk_mul_f32 v[32:33], v[96:97], v[32:33]
	v_pk_mul_f32 v[30:31], v[92:93], v[30:31]
	v_pk_mul_f32 v[28:29], v[94:95], v[28:29]
	v_pk_fma_f32 v[22:23], v[22:23], v[70:71], v[26:27]
	v_pk_fma_f32 v[26:27], v[20:21], v[68:69], v[32:33]
	v_pk_fma_f32 v[20:21], v[18:19], v[66:67], v[30:31]
	v_pk_fma_f32 v[24:25], v[24:25], v[72:73], v[28:29]
	v_mov_b32_e32 v28, v23
	v_mov_b32_e32 v29, v21
	v_mov_b32_e32 v18, v22
	v_mov_b32_e32 v19, v20
	v_pk_mul_f32 v[28:29], v[28:29], v[28:29]
	v_mov_b32_e32 v30, v25
	v_mov_b32_e32 v31, v27
	v_pk_fma_f32 v[18:19], v[18:19], v[18:19], v[28:29]
	v_mov_b32_e32 v28, v24
	v_mov_b32_e32 v29, v26
	v_pk_mul_f32 v[30:31], v[30:31], v[30:31]
	v_add_u32_e32 v34, 0x48100, v188
	v_pk_fma_f32 v[28:29], v[28:29], v[28:29], v[30:31]
	v_cvt_pk_bf16_f32 v20, v20, v21
	v_pk_add_f32 v[18:19], v[18:19], v[28:29]
	v_cvt_pk_bf16_f32 v21, v26, v27
	v_add_f32_e32 v18, v18, v19
	v_add_f32_e32 v18, v102, v18
	v_cvt_pk_bf16_f32 v19, v24, v25
	v_cvt_pk_bf16_f32 v18, v22, v23
	global_store_dwordx4 v34, v[18:21], s[96:97] sc1
	s_waitcnt vmcnt(7)
	v_lshlrev_b32_e32 v22, 16, v80
	v_and_b32_e32 v23, 0xffff0000, v80
	v_lshlrev_b32_e32 v18, 16, v78
	v_and_b32_e32 v19, 0xffff0000, v78
	v_lshlrev_b32_e32 v24, 16, v81
	v_and_b32_e32 v25, 0xffff0000, v81
	v_lshlrev_b32_e32 v20, 16, v79
	v_and_b32_e32 v21, 0xffff0000, v79
	v_pk_mul_f32 v[18:19], v[90:91], v[18:19]
	v_pk_mul_f32 v[24:25], v[96:97], v[24:25]
	v_pk_mul_f32 v[22:23], v[92:93], v[22:23]
	v_pk_mul_f32 v[20:21], v[94:95], v[20:21]
	v_pk_fma_f32 v[14:15], v[14:15], v[70:71], v[18:19]
	v_pk_fma_f32 v[18:19], v[12:13], v[68:69], v[24:25]
	v_pk_fma_f32 v[12:13], v[10:11], v[66:67], v[22:23]
	v_pk_fma_f32 v[16:17], v[16:17], v[72:73], v[20:21]
	v_mov_b32_e32 v20, v15
	v_mov_b32_e32 v21, v13
	v_mov_b32_e32 v10, v14
	v_mov_b32_e32 v11, v12
	v_pk_mul_f32 v[20:21], v[20:21], v[20:21]
	v_mov_b32_e32 v22, v17
	v_mov_b32_e32 v23, v19
	v_pk_fma_f32 v[10:11], v[10:11], v[10:11], v[20:21]
	v_mov_b32_e32 v20, v16
	v_mov_b32_e32 v21, v18
	v_pk_mul_f32 v[22:23], v[22:23], v[22:23]
	v_add_u32_e32 v26, 0x50100, v188
	v_pk_fma_f32 v[20:21], v[20:21], v[20:21], v[22:23]
	v_cvt_pk_bf16_f32 v12, v12, v13
	v_pk_add_f32 v[10:11], v[10:11], v[20:21]
	v_cvt_pk_bf16_f32 v13, v18, v19
	v_add_f32_e32 v10, v10, v11
	v_add_f32_e32 v10, v101, v10
	v_cvt_pk_bf16_f32 v11, v16, v17
	v_cvt_pk_bf16_f32 v10, v14, v15
	global_store_dwordx4 v26, v[10:13], s[96:97] sc1
	s_waitcnt vmcnt(7)
	v_lshlrev_b32_e32 v14, 16, v76
	v_and_b32_e32 v15, 0xffff0000, v76
	v_lshlrev_b32_e32 v10, 16, v74
	v_and_b32_e32 v11, 0xffff0000, v74
	v_lshlrev_b32_e32 v16, 16, v77
	v_and_b32_e32 v17, 0xffff0000, v77
	v_lshlrev_b32_e32 v12, 16, v75
	v_and_b32_e32 v13, 0xffff0000, v75
	v_pk_mul_f32 v[10:11], v[90:91], v[10:11]
	v_pk_mul_f32 v[16:17], v[96:97], v[16:17]
	v_pk_mul_f32 v[14:15], v[92:93], v[14:15]
	v_pk_mul_f32 v[12:13], v[94:95], v[12:13]
	v_pk_fma_f32 v[6:7], v[6:7], v[70:71], v[10:11]
	v_pk_fma_f32 v[10:11], v[4:5], v[68:69], v[16:17]
	v_pk_fma_f32 v[4:5], v[2:3], v[66:67], v[14:15]
	v_pk_fma_f32 v[8:9], v[8:9], v[72:73], v[12:13]
	v_mov_b32_e32 v12, v7
	v_mov_b32_e32 v13, v5
	v_mov_b32_e32 v2, v6
	v_mov_b32_e32 v3, v4
	v_pk_mul_f32 v[12:13], v[12:13], v[12:13]
	v_mov_b32_e32 v14, v9
	v_mov_b32_e32 v15, v11
	v_pk_fma_f32 v[2:3], v[2:3], v[2:3], v[12:13]
	v_mov_b32_e32 v12, v8
	v_mov_b32_e32 v13, v10
	v_pk_mul_f32 v[14:15], v[14:15], v[14:15]
	v_add_u32_e32 v18, 0x58100, v188
	v_pk_fma_f32 v[12:13], v[12:13], v[12:13], v[14:15]
	v_cvt_pk_bf16_f32 v4, v4, v5
	v_pk_add_f32 v[2:3], v[2:3], v[12:13]
	v_cvt_pk_bf16_f32 v5, v10, v11
	v_add_f32_e32 v2, v2, v3
	v_add_f32_e32 v2, v100, v2
	v_cvt_pk_bf16_f32 v3, v8, v9
	v_cvt_pk_bf16_f32 v2, v6, v7
	global_store_dwordx4 v18, v[2:5], s[96:97] sc1
	s_cbranch_vccnz .LBB0_1517
	s_andn2_b64 vcc, exec, s[22:23]
	s_cbranch_vccnz .LBB0_1516
	s_barrier
	s_branch .LBB0_1516
